# leading-half epilogue priority raise extended to the D1, projection, V^T and output-projection epilogues (reset at GLA-prep entry)
# speedup vs baseline: 1.0100x; 1.0003x over previous
; #define PG8_STAGE(bufoff, gbase, voff) do { _Pragma("unroll") for (int _i = 0; _i < 2; ++_i) \
;         __builtin_amdgcn_global_load_lds((const unsigned*)((const char*)(gbase) + (voff)[_i]), (PG8_LAS unsigned*)(lds + (bufoff) + ldsw + _i * 8192), 16, 0, 0); } while (0)
; #define PG8_LDA(dst, b, h) do { _Pragma("unroll") for (int m = 0; m < 4; ++m) _Pragma("unroll") for (int k = 0; k < 2; ++k) dst[m][k] = *(const PG8_LAS bf16x8*)(lds + PG8_SA(b, h) + aoff + m * 2048 + k * 1024); } while (0)
; #define PG8_LDB(dst, b, h) do { _Pragma("unroll") for (int n = 0; n < 2; ++n) _Pragma("unroll") for (int k = 0; k < 2; ++k) dst[n][k] = *(const PG8_LAS bf16x8*)(lds + PG8_SB(b, h) + boff + n * 2048 + k * 1024); } while (0)
; #define PG8_MMA_NP(ai, bj, At, Bt) do { _Pragma("unroll") for (int m = 0; m < 4; ++m) _Pragma("unroll") for (int n = 0; n < 2; ++n) _Pragma("unroll") for (int k = 0; k < 2; ++k) \
;         acc[ai][bj][m][n] = __builtin_amdgcn_mfma_f32_16x16x32_bf16(Bt[n][k], At[m][k], acc[ai][bj][m][n], 0, 0, 0); } while (0)
; #define PG8_WAIT_V(n) asm volatile("s_waitcnt vmcnt(" #n ")" ::: "memory")
; #define PG8_WAIT_L(n) asm volatile("s_waitcnt lgkmcnt(" #n ")" ::: "memory")
; #define PG8_BAR __builtin_amdgcn_s_barrier()
; #define PG8_SCHED __builtin_amdgcn_sched_barrier(0)
; template <class Epi, class Sched, bool ALIGN_EPI = false, bool SP2 = false>
; __device__ __forceinline__ void gemm_phase(PG8_LAS unsigned char* lds, const Gemm g, const Sched& S, const Epi& E) {
;     ...
;             PG8_LDB(B0, 0, 0); PG8_LDB(B1, 0, 1); PG8_SCHED; PG8_LDA(At, 0, 0); PG8_STAGE(PG8_SA(1, 1), a1 + hstep, voffA);
;             PG8_WAIT_V(8); PG8_WAIT_L(0); PG8_BAR; __builtin_amdgcn_s_setprio(1); PG8_MMA_NP(0, 0, At, B0); PG8_MMA_NP(0, 1, At, B1); __builtin_amdgcn_s_setprio(0); PG8_BAR; PG8_SCHED;
;             PG8_LDA(At, 0, 1); PG8_STAGE(PG8_SB(0, 0), b2, voffB); PG8_STAGE(PG8_SB(0, 1), b2 + hstep, voffB); PG8_STAGE(PG8_SA(0, 0), a2, voffA);
;             PG8_WAIT_V(8); PG8_WAIT_L(0); PG8_BAR; __builtin_amdgcn_s_setprio(1); PG8_MMA_NP(1, 0, At, B0); PG8_MMA_NP(1, 1, At, B1); __builtin_amdgcn_s_setprio(0); PG8_BAR; PG8_SCHED;
.LBB0_194:
	s_add_u32 s40, s12, 0x100
	s_addc_u32 s41, s13, 0
	s_add_i32 s22, 0, 0x10000
	s_cmp_eq_u32 s70, 40
	s_cselect_b32 s47, s55, s41
	s_cselect_b32 s46, s54, s40
	s_cselect_b32 s15, s57, s69
	s_cselect_b32 s14, s56, s59
	s_add_i32 s23, 0, 0x14000
	v_add_u32_e32 v152, s22, v161
	v_add_u32_e32 v186, s23, v161
	ds_read_b128 v[130:133], v152
	ds_read_b128 v[134:137], v152 offset:1024
	ds_read_b128 v[148:151], v152 offset:2048
	ds_read_b128 v[152:155], v152 offset:3072
	ds_read_b128 v[156:159], v186
	ds_read_b128 v[178:181], v186 offset:1024
	ds_read_b128 v[182:185], v186 offset:2048
	ds_read_b128 v[186:189], v186 offset:3072
	v_lshl_add_u64 v[190:191], s[12:13], 0, v[144:145]
	s_add_i32 m0, s31, 0xc000
	ds_read_b128 v[202:205], v163
	ds_read_b128 v[206:209], v163 offset:1024
	ds_read_b128 v[210:213], v163 offset:2048
	ds_read_b128 v[214:217], v163 offset:3072
	ds_read_b128 v[218:221], v163 offset:4096
	ds_read_b128 v[222:225], v163 offset:5120
	ds_read_b128 v[226:229], v163 offset:6144
	ds_read_b128 v[230:233], v163 offset:7168
	global_load_lds_dwordx4 v[190:191], off
	v_lshl_add_u64 v[190:191], s[12:13], 0, v[146:147]
	s_add_i32 m0, s31, 0xe000
	s_nop 0
	global_load_lds_dwordx4 v[190:191], off
	s_waitcnt vmcnt(8)
	s_waitcnt lgkmcnt(0)
	s_barrier
	s_setprio 1
	s_waitcnt lgkmcnt(0)
	v_mfma_f32_16x16x32_bf16 v[126:129], v[130:133], v[202:205], v[126:129]
	v_mfma_f32_16x16x32_bf16 v[122:125], v[148:151], v[202:205], v[122:125]
	v_mfma_f32_16x16x32_bf16 v[110:113], v[130:133], v[210:213], v[110:113]
	v_mfma_f32_16x16x32_bf16 v[106:109], v[148:151], v[210:213], v[106:109]
	v_mfma_f32_16x16x32_bf16 v[94:97], v[130:133], v[218:221], v[94:97]
	v_mfma_f32_16x16x32_bf16 v[90:93], v[148:151], v[218:221], v[90:93]
	v_mfma_f32_16x16x32_bf16 v[78:81], v[130:133], v[226:229], v[78:81]
	v_mfma_f32_16x16x32_bf16 v[74:77], v[148:151], v[226:229], v[74:77]
	v_mfma_f32_16x16x32_bf16 v[118:121], v[156:159], v[202:205], v[118:121]
	v_mfma_f32_16x16x32_bf16 v[114:117], v[182:185], v[202:205], v[114:117]
	v_mfma_f32_16x16x32_bf16 v[102:105], v[156:159], v[210:213], v[102:105]
	v_mfma_f32_16x16x32_bf16 v[98:101], v[182:185], v[210:213], v[98:101]
	v_mfma_f32_16x16x32_bf16 v[86:89], v[156:159], v[218:221], v[86:89]
	v_mfma_f32_16x16x32_bf16 v[82:85], v[182:185], v[218:221], v[82:85]
	v_mfma_f32_16x16x32_bf16 v[70:73], v[156:159], v[226:229], v[70:73]
	v_mfma_f32_16x16x32_bf16 v[66:69], v[182:185], v[226:229], v[66:69]
	v_mfma_f32_16x16x32_bf16 v[126:129], v[134:137], v[206:209], v[126:129]
	v_mfma_f32_16x16x32_bf16 v[122:125], v[152:155], v[206:209], v[122:125]
	v_mfma_f32_16x16x32_bf16 v[110:113], v[134:137], v[214:217], v[110:113]
	v_mfma_f32_16x16x32_bf16 v[106:109], v[152:155], v[214:217], v[106:109]
	v_mfma_f32_16x16x32_bf16 v[94:97], v[134:137], v[222:225], v[94:97]
	v_mfma_f32_16x16x32_bf16 v[90:93], v[152:155], v[222:225], v[90:93]
	v_mfma_f32_16x16x32_bf16 v[78:81], v[134:137], v[230:233], v[78:81]
	v_mfma_f32_16x16x32_bf16 v[74:77], v[152:155], v[230:233], v[74:77]
	v_mfma_f32_16x16x32_bf16 v[118:121], v[178:181], v[206:209], v[118:121]
	v_mfma_f32_16x16x32_bf16 v[114:117], v[186:189], v[206:209], v[114:117]
	v_mfma_f32_16x16x32_bf16 v[102:105], v[178:181], v[214:217], v[102:105]
	v_mfma_f32_16x16x32_bf16 v[98:101], v[186:189], v[214:217], v[98:101]
	v_mfma_f32_16x16x32_bf16 v[86:89], v[178:181], v[222:225], v[86:89]
	v_mfma_f32_16x16x32_bf16 v[82:85], v[186:189], v[222:225], v[82:85]
	v_mfma_f32_16x16x32_bf16 v[70:73], v[178:181], v[230:233], v[70:73]
	v_mfma_f32_16x16x32_bf16 v[66:69], v[186:189], v[230:233], v[66:69]
	s_setprio 0
	s_barrier
	s_add_i32 s12, s22, s10
	v_lshl_add_u64 v[190:191], s[14:15], 0, v[0:1]
	s_mov_b32 m0, s12
	ds_read_b128 v[202:205], v163 offset:16384
	ds_read_b128 v[206:209], v163 offset:17408
	ds_read_b128 v[210:213], v163 offset:18432
	ds_read_b128 v[214:217], v163 offset:19456
	ds_read_b128 v[218:221], v163 offset:20480
	ds_read_b128 v[222:225], v163 offset:21504
	ds_read_b128 v[226:229], v163 offset:22528
	ds_read_b128 v[230:233], v163 offset:23552
	global_load_lds_dwordx4 v[190:191], off
	s_add_i32 m0, s12, 0x2000
	s_add_u32 s12, s14, 0xb0000
	v_lshl_add_u64 v[234:235], s[14:15], 0, v[138:139]
	s_addc_u32 s13, s15, 0
	s_add_i32 s22, s23, s10
	global_load_lds_dwordx4 v[234:235], off
	v_lshl_add_u64 v[236:237], s[12:13], 0, v[0:1]
	s_mov_b32 m0, s22
	v_lshl_add_u64 v[238:239], s[46:47], 0, v[140:141]
	global_load_lds_dwordx4 v[236:237], off
	v_lshl_add_u64 v[236:237], s[12:13], 0, v[138:139]
	s_add_i32 m0, s22, 0x2000
	s_nop 0
	global_load_lds_dwordx4 v[236:237], off
	v_lshl_add_u64 v[236:237], s[46:47], 0, v[142:143]
	s_mov_b32 m0, s31
	s_nop 0
	global_load_lds_dwordx4 v[236:237], off
	s_mov_b32 m0, s60
	s_nop 0
	global_load_lds_dwordx4 v[238:239], off
	s_waitcnt vmcnt(8)
	s_waitcnt lgkmcnt(0)
	s_barrier
; #define PG8_STAGE(bufoff, gbase, voff) do { _Pragma("unroll") for (int _i = 0; _i < 2; ++_i) \
;         __builtin_amdgcn_global_load_lds((const unsigned*)((const char*)(gbase) + (voff)[_i]), (PG8_LAS unsigned*)(lds + (bufoff) + ldsw + _i * 8192), 16, 0, 0); } while (0)
; #define PG8_LDA(dst, b, h) do { _Pragma("unroll") for (int m = 0; m < 4; ++m) _Pragma("unroll") for (int k = 0; k < 2; ++k) dst[m][k] = *(const PG8_LAS bf16x8*)(lds + PG8_SA(b, h) + aoff + m * 2048 + k * 1024); } while (0)
; #define PG8_LDB(dst, b, h) do { _Pragma("unroll") for (int n = 0; n < 2; ++n) _Pragma("unroll") for (int k = 0; k < 2; ++k) dst[n][k] = *(const PG8_LAS bf16x8*)(lds + PG8_SB(b, h) + boff + n * 2048 + k * 1024); } while (0)
; #define PG8_MMA_NP(ai, bj, At, Bt) do { _Pragma("unroll") for (int m = 0; m < 4; ++m) _Pragma("unroll") for (int n = 0; n < 2; ++n) _Pragma("unroll") for (int k = 0; k < 2; ++k) \
;         acc[ai][bj][m][n] = __builtin_amdgcn_mfma_f32_16x16x32_bf16(Bt[n][k], At[m][k], acc[ai][bj][m][n], 0, 0, 0); } while (0)
; #define PG8_WAIT_V(n) asm volatile("s_waitcnt vmcnt(" #n ")" ::: "memory")
; #define PG8_WAIT_L(n) asm volatile("s_waitcnt lgkmcnt(" #n ")" ::: "memory")
; #define PG8_BAR __builtin_amdgcn_s_barrier()
; #define PG8_SCHED __builtin_amdgcn_sched_barrier(0)
; template <class Epi, class Sched, bool ALIGN_EPI = false, bool SP2 = false>
; __device__ __forceinline__ void gemm_phase(PG8_LAS unsigned char* lds, const Gemm g, const Sched& S, const Epi& E) {
;     ...
;             PG8_WAIT_V(8); PG8_WAIT_L(0); PG8_BAR; __builtin_amdgcn_s_setprio(1); PG8_MMA_NP(1, 0, At, B0); PG8_MMA_NP(1, 1, At, B1); __builtin_amdgcn_s_setprio(0); PG8_BAR; PG8_SCHED;
;             PG8_LDB(B0, 1, 0); PG8_LDB(B1, 1, 1); PG8_SCHED; PG8_LDA(At, 1, 0); PG8_STAGE(PG8_SA(0, 1), a2 + hstep, voffA);
;             PG8_WAIT_V(8); PG8_WAIT_L(0); PG8_BAR; __builtin_amdgcn_s_setprio(1); PG8_MMA_NP(0, 0, At, B0); PG8_MMA_NP(0, 1, At, B1); __builtin_amdgcn_s_setprio(0); PG8_BAR; PG8_SCHED;
	s_setprio 1
	s_waitcnt lgkmcnt(0)
	v_mfma_f32_16x16x32_bf16 v[62:65], v[130:133], v[202:205], v[62:65]
	v_mfma_f32_16x16x32_bf16 v[58:61], v[148:151], v[202:205], v[58:61]
	v_mfma_f32_16x16x32_bf16 v[46:49], v[130:133], v[210:213], v[46:49]
	v_mfma_f32_16x16x32_bf16 v[42:45], v[148:151], v[210:213], v[42:45]
	v_mfma_f32_16x16x32_bf16 v[30:33], v[130:133], v[218:221], v[30:33]
	v_mfma_f32_16x16x32_bf16 v[26:29], v[148:151], v[218:221], v[26:29]
	v_mfma_f32_16x16x32_bf16 v[14:17], v[130:133], v[226:229], v[14:17]
	v_mfma_f32_16x16x32_bf16 v[10:13], v[148:151], v[226:229], v[10:13]
	v_mfma_f32_16x16x32_bf16 v[54:57], v[156:159], v[202:205], v[54:57]
	v_mfma_f32_16x16x32_bf16 v[50:53], v[182:185], v[202:205], v[50:53]
	v_mfma_f32_16x16x32_bf16 v[38:41], v[156:159], v[210:213], v[38:41]
	v_mfma_f32_16x16x32_bf16 v[34:37], v[182:185], v[210:213], v[34:37]
	v_mfma_f32_16x16x32_bf16 v[22:25], v[156:159], v[218:221], v[22:25]
	v_mfma_f32_16x16x32_bf16 v[18:21], v[182:185], v[218:221], v[18:21]
	v_mfma_f32_16x16x32_bf16 v[6:9], v[156:159], v[226:229], v[6:9]
	v_mfma_f32_16x16x32_bf16 v[2:5], v[182:185], v[226:229], v[2:5]
	v_mfma_f32_16x16x32_bf16 v[62:65], v[134:137], v[206:209], v[62:65]
	v_mfma_f32_16x16x32_bf16 v[58:61], v[152:155], v[206:209], v[58:61]
	v_mfma_f32_16x16x32_bf16 v[46:49], v[134:137], v[214:217], v[46:49]
	v_mfma_f32_16x16x32_bf16 v[42:45], v[152:155], v[214:217], v[42:45]
	v_mfma_f32_16x16x32_bf16 v[30:33], v[134:137], v[222:225], v[30:33]
	v_mfma_f32_16x16x32_bf16 v[26:29], v[152:155], v[222:225], v[26:29]
	v_mfma_f32_16x16x32_bf16 v[14:17], v[134:137], v[230:233], v[14:17]
	v_mfma_f32_16x16x32_bf16 v[10:13], v[152:155], v[230:233], v[10:13]
	v_mfma_f32_16x16x32_bf16 v[54:57], v[178:181], v[206:209], v[54:57]
	v_mfma_f32_16x16x32_bf16 v[50:53], v[186:189], v[206:209], v[50:53]
	v_mfma_f32_16x16x32_bf16 v[38:41], v[178:181], v[214:217], v[38:41]
	v_mfma_f32_16x16x32_bf16 v[34:37], v[186:189], v[214:217], v[34:37]
	v_mfma_f32_16x16x32_bf16 v[22:25], v[178:181], v[222:225], v[22:25]
	v_mfma_f32_16x16x32_bf16 v[18:21], v[186:189], v[222:225], v[18:21]
	v_mfma_f32_16x16x32_bf16 v[6:9], v[178:181], v[230:233], v[6:9]
	v_mfma_f32_16x16x32_bf16 v[2:5], v[186:189], v[230:233], v[2:5]
	s_setprio 0
	s_barrier
	s_add_i32 s22, 0, 0x18000
	s_add_i32 s23, 0, 0x1c000
	v_add_u32_e32 v152, s22, v161
	v_add_u32_e32 v186, s23, v161
	ds_read_b128 v[130:133], v152
	ds_read_b128 v[134:137], v152 offset:1024
	ds_read_b128 v[148:151], v152 offset:2048
	ds_read_b128 v[152:155], v152 offset:3072
	ds_read_b128 v[156:159], v186
	ds_read_b128 v[178:181], v186 offset:1024
	ds_read_b128 v[182:185], v186 offset:2048
	ds_read_b128 v[186:189], v186 offset:3072
	s_add_u32 s12, s46, 0xb0000
	s_addc_u32 s13, s47, 0
	s_mov_b32 m0, s61
	v_lshl_add_u64 v[240:241], s[12:13], 0, v[142:143]
	ds_read_b128 v[202:205], v163 offset:32768
	ds_read_b128 v[206:209], v163 offset:33792
	ds_read_b128 v[210:213], v163 offset:34816
	ds_read_b128 v[214:217], v163 offset:35840
	ds_read_b128 v[218:221], v163 offset:36864
	ds_read_b128 v[222:225], v163 offset:37888
	ds_read_b128 v[226:229], v163 offset:38912
	ds_read_b128 v[230:233], v163 offset:39936
	global_load_lds_dwordx4 v[240:241], off
	v_lshl_add_u64 v[240:241], s[12:13], 0, v[140:141]
	s_mov_b32 m0, s62
	s_nop 0
	global_load_lds_dwordx4 v[240:241], off
	s_waitcnt vmcnt(8)
	s_waitcnt lgkmcnt(0)
	s_barrier
	s_setprio 1
	s_waitcnt lgkmcnt(0)
	v_mfma_f32_16x16x32_bf16 v[126:129], v[130:133], v[202:205], v[126:129]
	v_mfma_f32_16x16x32_bf16 v[122:125], v[148:151], v[202:205], v[122:125]
	v_mfma_f32_16x16x32_bf16 v[110:113], v[130:133], v[210:213], v[110:113]
	v_mfma_f32_16x16x32_bf16 v[106:109], v[148:151], v[210:213], v[106:109]
	v_mfma_f32_16x16x32_bf16 v[94:97], v[130:133], v[218:221], v[94:97]
	v_mfma_f32_16x16x32_bf16 v[90:93], v[148:151], v[218:221], v[90:93]
	v_mfma_f32_16x16x32_bf16 v[78:81], v[130:133], v[226:229], v[78:81]
	v_mfma_f32_16x16x32_bf16 v[74:77], v[148:151], v[226:229], v[74:77]
	v_mfma_f32_16x16x32_bf16 v[118:121], v[156:159], v[202:205], v[118:121]
	v_mfma_f32_16x16x32_bf16 v[114:117], v[182:185], v[202:205], v[114:117]
	v_mfma_f32_16x16x32_bf16 v[102:105], v[156:159], v[210:213], v[102:105]
	v_mfma_f32_16x16x32_bf16 v[98:101], v[182:185], v[210:213], v[98:101]
	v_mfma_f32_16x16x32_bf16 v[86:89], v[156:159], v[218:221], v[86:89]
	v_mfma_f32_16x16x32_bf16 v[82:85], v[182:185], v[218:221], v[82:85]
	v_mfma_f32_16x16x32_bf16 v[70:73], v[156:159], v[226:229], v[70:73]
	v_mfma_f32_16x16x32_bf16 v[66:69], v[182:185], v[226:229], v[66:69]
	v_mfma_f32_16x16x32_bf16 v[126:129], v[134:137], v[206:209], v[126:129]
	v_mfma_f32_16x16x32_bf16 v[122:125], v[152:155], v[206:209], v[122:125]
	v_mfma_f32_16x16x32_bf16 v[110:113], v[134:137], v[214:217], v[110:113]
	v_mfma_f32_16x16x32_bf16 v[106:109], v[152:155], v[214:217], v[106:109]
	v_mfma_f32_16x16x32_bf16 v[94:97], v[134:137], v[222:225], v[94:97]
	v_mfma_f32_16x16x32_bf16 v[90:93], v[152:155], v[222:225], v[90:93]
	v_mfma_f32_16x16x32_bf16 v[78:81], v[134:137], v[230:233], v[78:81]
	v_mfma_f32_16x16x32_bf16 v[74:77], v[152:155], v[230:233], v[74:77]
	v_mfma_f32_16x16x32_bf16 v[118:121], v[178:181], v[206:209], v[118:121]
	v_mfma_f32_16x16x32_bf16 v[114:117], v[186:189], v[206:209], v[114:117]
	v_mfma_f32_16x16x32_bf16 v[102:105], v[178:181], v[214:217], v[102:105]
	v_mfma_f32_16x16x32_bf16 v[98:101], v[186:189], v[214:217], v[98:101]
	v_mfma_f32_16x16x32_bf16 v[86:89], v[178:181], v[222:225], v[86:89]
	v_mfma_f32_16x16x32_bf16 v[82:85], v[186:189], v[222:225], v[82:85]
	v_mfma_f32_16x16x32_bf16 v[70:73], v[178:181], v[230:233], v[70:73]
	v_mfma_f32_16x16x32_bf16 v[66:69], v[186:189], v[230:233], v[66:69]
	s_setprio 0
	s_barrier
; #define PG8_STAGE(bufoff, gbase, voff) do { _Pragma("unroll") for (int _i = 0; _i < 2; ++_i) \
;         __builtin_amdgcn_global_load_lds((const unsigned*)((const char*)(gbase) + (voff)[_i]), (PG8_LAS unsigned*)(lds + (bufoff) + ldsw + _i * 8192), 16, 0, 0); } while (0)
; #define PG8_LDA(dst, b, h) do { _Pragma("unroll") for (int m = 0; m < 4; ++m) _Pragma("unroll") for (int k = 0; k < 2; ++k) dst[m][k] = *(const PG8_LAS bf16x8*)(lds + PG8_SA(b, h) + aoff + m * 2048 + k * 1024); } while (0)
; #define PG8_MMA_NP(ai, bj, At, Bt) do { _Pragma("unroll") for (int m = 0; m < 4; ++m) _Pragma("unroll") for (int n = 0; n < 2; ++n) _Pragma("unroll") for (int k = 0; k < 2; ++k) \
;         acc[ai][bj][m][n] = __builtin_amdgcn_mfma_f32_16x16x32_bf16(Bt[n][k], At[m][k], acc[ai][bj][m][n], 0, 0, 0); } while (0)
; #define PG8_WAIT_V(n) asm volatile("s_waitcnt vmcnt(" #n ")" ::: "memory")
; #define PG8_WAIT_L(n) asm volatile("s_waitcnt lgkmcnt(" #n ")" ::: "memory")
; #define PG8_BAR __builtin_amdgcn_s_barrier()
; #define PG8_SCHED __builtin_amdgcn_sched_barrier(0)
; template <class Epi, class Sched, bool ALIGN_EPI = false, bool SP2 = false>
; __device__ __forceinline__ void gemm_phase(PG8_LAS unsigned char* lds, const Gemm g, const Sched& S, const Epi& E) {
;     ...
;             PG8_LDA(At, 1, 1); PG8_STAGE(PG8_SB(1, 0), b3, voffB); PG8_STAGE(PG8_SB(1, 1), b3 + hstep, voffB); PG8_STAGE(PG8_SA(1, 0), a3, voffA);
;             PG8_WAIT_V(8); PG8_WAIT_L(0); PG8_BAR; __builtin_amdgcn_s_setprio(1); PG8_MMA_NP(1, 0, At, B0); PG8_MMA_NP(1, 1, At, B1); __builtin_amdgcn_s_setprio(0); PG8_BAR; PG8_SCHED;
;     ...
;         if constexpr (ALIGN_EPI) { if (wr == 0) PG8_BAR; }
	s_add_i32 s12, s22, s10
	v_lshl_add_u64 v[190:191], v[190:191], 0, s[20:21]
	s_mov_b32 m0, s12
	ds_read_b128 v[202:205], v163 offset:49152
	ds_read_b128 v[206:209], v163 offset:50176
	ds_read_b128 v[210:213], v163 offset:51200
	ds_read_b128 v[214:217], v163 offset:52224
	ds_read_b128 v[218:221], v163 offset:53248
	ds_read_b128 v[222:225], v163 offset:54272
	ds_read_b128 v[226:229], v163 offset:55296
	ds_read_b128 v[230:233], v163 offset:56320
	global_load_lds_dwordx4 v[190:191], off
	s_add_i32 m0, s12, 0x2000
	s_add_u32 s12, s14, 0xb0080
	v_lshl_add_u64 v[190:191], v[234:235], 0, s[20:21]
	s_addc_u32 s13, s15, 0
	s_add_i32 s14, s23, s10
	global_load_lds_dwordx4 v[190:191], off
	v_lshl_add_u64 v[190:191], s[12:13], 0, v[0:1]
	s_mov_b32 m0, s14
	s_nop 0
	global_load_lds_dwordx4 v[190:191], off
	v_lshl_add_u64 v[190:191], s[12:13], 0, v[138:139]
	s_add_i32 m0, s14, 0x2000
	s_nop 0
	global_load_lds_dwordx4 v[190:191], off
	v_lshl_add_u64 v[190:191], v[236:237], 0, s[20:21]
	s_mov_b32 m0, s64
	s_nop 0
	global_load_lds_dwordx4 v[190:191], off
	v_lshl_add_u64 v[190:191], v[238:239], 0, s[20:21]
	s_mov_b32 m0, s65
	s_nop 0
	global_load_lds_dwordx4 v[190:191], off
	s_waitcnt vmcnt(8)
	s_waitcnt lgkmcnt(0)
	s_barrier
	s_setprio 1
	s_waitcnt lgkmcnt(0)
	v_mfma_f32_16x16x32_bf16 v[62:65], v[130:133], v[202:205], v[62:65]
	v_mfma_f32_16x16x32_bf16 v[58:61], v[148:151], v[202:205], v[58:61]
	v_mfma_f32_16x16x32_bf16 v[46:49], v[130:133], v[210:213], v[46:49]
	v_mfma_f32_16x16x32_bf16 v[42:45], v[148:151], v[210:213], v[42:45]
	v_mfma_f32_16x16x32_bf16 v[30:33], v[130:133], v[218:221], v[30:33]
	v_mfma_f32_16x16x32_bf16 v[26:29], v[148:151], v[218:221], v[26:29]
	v_mfma_f32_16x16x32_bf16 v[14:17], v[130:133], v[226:229], v[14:17]
	v_mfma_f32_16x16x32_bf16 v[10:13], v[148:151], v[226:229], v[10:13]
	v_mfma_f32_16x16x32_bf16 v[54:57], v[156:159], v[202:205], v[54:57]
	v_mfma_f32_16x16x32_bf16 v[50:53], v[182:185], v[202:205], v[50:53]
	v_mfma_f32_16x16x32_bf16 v[38:41], v[156:159], v[210:213], v[38:41]
	v_mfma_f32_16x16x32_bf16 v[34:37], v[182:185], v[210:213], v[34:37]
	v_mfma_f32_16x16x32_bf16 v[22:25], v[156:159], v[218:221], v[22:25]
	v_mfma_f32_16x16x32_bf16 v[18:21], v[182:185], v[218:221], v[18:21]
	v_mfma_f32_16x16x32_bf16 v[6:9], v[156:159], v[226:229], v[6:9]
	v_mfma_f32_16x16x32_bf16 v[2:5], v[182:185], v[226:229], v[2:5]
	v_mfma_f32_16x16x32_bf16 v[62:65], v[134:137], v[206:209], v[62:65]
	v_mfma_f32_16x16x32_bf16 v[58:61], v[152:155], v[206:209], v[58:61]
	v_mfma_f32_16x16x32_bf16 v[46:49], v[134:137], v[214:217], v[46:49]
	v_mfma_f32_16x16x32_bf16 v[42:45], v[152:155], v[214:217], v[42:45]
	v_mfma_f32_16x16x32_bf16 v[30:33], v[134:137], v[222:225], v[30:33]
	v_mfma_f32_16x16x32_bf16 v[26:29], v[152:155], v[222:225], v[26:29]
	v_mfma_f32_16x16x32_bf16 v[14:17], v[134:137], v[230:233], v[14:17]
	v_mfma_f32_16x16x32_bf16 v[10:13], v[152:155], v[230:233], v[10:13]
	v_mfma_f32_16x16x32_bf16 v[54:57], v[178:181], v[206:209], v[54:57]
	v_mfma_f32_16x16x32_bf16 v[50:53], v[186:189], v[206:209], v[50:53]
	v_mfma_f32_16x16x32_bf16 v[38:41], v[178:181], v[214:217], v[38:41]
	v_mfma_f32_16x16x32_bf16 v[34:37], v[186:189], v[214:217], v[34:37]
	v_mfma_f32_16x16x32_bf16 v[22:25], v[178:181], v[222:225], v[22:25]
	v_mfma_f32_16x16x32_bf16 v[18:21], v[186:189], v[222:225], v[18:21]
	v_mfma_f32_16x16x32_bf16 v[6:9], v[178:181], v[230:233], v[6:9]
	v_mfma_f32_16x16x32_bf16 v[2:5], v[186:189], v[230:233], v[2:5]
	s_setprio 0
	s_barrier
	s_add_i32 s70, s70, 2
	s_add_u32 s59, s59, 0x100
	s_addc_u32 s69, s69, 0
	s_cmp_gt_u32 s70, 41
	s_mov_b64 s[12:13], s[40:41]
	s_cbranch_scc0 .LBB0_194
	s_and_b64 vcc, exec, s[50:51]
	s_cbranch_vccz .LBB0_197
	s_barrier
	s_setprio 2

; DI void row_rstd(const float* ssq, int row0, int fq, float (&rs)[2][4]) {
; #pragma unroll
;     for (int ai = 0; ai < 2; ++ai)
; #pragma unroll
;         for (int m = 0; m < 4; ++m) {
;             const f32x4 v = *(const f32x4*)(ssq + (size_t)(row0 + ai * 128 + m * 16) * 16 + 4 * fq);
;     DI void operator()(const f32x4 (&acc)[2][2][4][2], const pg8::Unit& u, int wr, int wc, int fr, int fq) const {
;         const int row0 = u.pm * 256 + wr * 64 + fr; const int pn = u.pn;
;         float rs[2][4]; row_rstd(ssq, row0, fq, rs);
.Lkexit_2:
	v_lshl_add_u32 v240, s45, 8, v190
	v_ashrrev_i32_e32 v241, 31, v240
	v_add_u32_e32 v242, 0x80, v240
	v_ashrrev_i32_e32 v243, 31, v242
	v_lshlrev_b64 v[240:241], 6, v[240:241]
	v_lshlrev_b64 v[242:243], 6, v[242:243]
	v_lshl_add_u64 v[240:241], v[140:141], 0, v[240:241]
	v_lshl_add_u64 v[242:243], v[140:141], 0, v[242:243]
	global_load_dwordx4 v[208:211], v[240:241], off
	global_load_dwordx4 v[212:215], v[240:241], off offset:1024
	global_load_dwordx4 v[216:219], v[240:241], off offset:2048
	global_load_dwordx4 v[220:223], v[240:241], off offset:3072
	global_load_dwordx4 v[224:227], v[242:243], off
	global_load_dwordx4 v[228:231], v[242:243], off offset:1024
	global_load_dwordx4 v[232:235], v[242:243], off offset:2048
	global_load_dwordx4 v[236:239], v[242:243], off offset:3072
	s_and_b64 vcc, exec, s[38:39]
	s_cbranch_vccz .LBB0_373
	s_barrier
	s_setprio 2

; #define PG8_BAR __builtin_amdgcn_s_barrier()
; template <class Epi, class Sched, bool ALIGN_EPI = false, bool SP2 = false>
; __device__ __forceinline__ void gemm_phase(PG8_LAS unsigned char* lds, const Gemm g, const Sched& S, const Epi& E) {
;     ...
;         if constexpr (ALIGN_EPI) { if (wr == 0) PG8_BAR; }
;     DI void operator()(const f32x4 (&acc)[2][2][4][2], const pg8::Unit& u, int wr, int wc, int fr, int fq) const {
;         const int row0 = u.pm * 256 + wr * 64 + fr, tok0 = u.pn * 256 + wc * 32 + 8 * fq;
.Lkexit_3:
	s_and_b64 vcc, exec, s[44:45]
	s_cbranch_vccz .LBB0_435
	s_barrier
	s_setprio 2

; #define INP(i) ((const float*)karg(8 * (i)))
; DI void gla_prep_item(const Args& A, int l, unsigned char* ldsb, int item, int tid, bool stage) {
;     ...
;     const int c = item & 63, bh = item >> 6, h = bh & 3, b = bh >> 2;
;     const size_t tok0 = (size_t)b * SEQ + c * 64;
;     const int t = tid >> 3, dg = tid & 7;
;     const u32x4* cp = (const u32x4*)(CODES + (tok0 + t) * 32);
;     const u32x4 cq0 = cp[0], cq1 = cp[1], cq2 = cp[2], cq3 = cp[3];
;     const u32x4 qv = *(const u32x4*)(GQK + (tok0 + t) * 512 + h * 64 + 8 * dg), kv = *(const u32x4*)(GQK + (tok0 + t) * 512 + 256 + h * 64 + 8 * dg);
;     if (stage) {
;         const int idx = tid * 4, dir = idx >> 10, r = (idx >> 6) & 15, d = idx & 63;
;         const float* w = (dir ? INP(11) : INP(9)) + (size_t)l * 16 * 256 + r * 256 + h * 64 + d;
;         *(f32x4*)(wg + idx) = *(const f32x4*)w;
;         if (tid < 128) { const int dr = tid >> 6, dd = tid & 63; bg[tid] = (dr ? INP(12) : INP(10))[l * 256 + h * 64 + dd]; }
; __global__ void __launch_bounds__(NWAVES * 64, 2) fwd_megakernel(Args A) {
;     ...
;         for (int rep = 0; rep < REP_PREP; ++rep) { LAUNDER_TID int ph_ = -1; for (int k = xl ? rk : vcu; k < (xl ? 256 : 2048); k += (xl ? nl : G)) { const int li = (xl && nl == 32) ? (((rk >> 3) << 6) | ((rk & 7) + 8 * ((k - rk) >> 5))) : k;     const int it = xl ? ((((xq << 2) | (li >> 6)) << 6) | (li & 63)) : k; const int h_ = (it >> 6) & 3; gla_prep_item(A, l, lds, it, tid, h_ != ph_); ph_ = h_; } }
.LBB0_557:
	s_setprio 0
	v_readlane_b32 s2, v245, 1
	v_readlane_b32 s3, v245, 2
	v_mov_b32_e32 v0, v165
	s_and_b64 vcc, exec, s[2:3]
	s_cbranch_vccz .LBB0_592
	s_movk_i32 s2, 0xff
	v_and_b32_e32 v6, 63, v0
	v_ashrrev_i32_e32 v7, 6, v0
	v_lshrrev_b32_e32 v9, 2, v0
	v_cmp_lt_u32_e64 s[42:43], s2, v0
	s_movk_i32 s2, 0x80
	v_and_b32_e32 v8, 3, v7
	v_and_b32_e32 v9, 0x3fffffc0, v9
	v_lshlrev_b32_e32 v10, 2, v6
	v_ashrrev_i32_e32 v26, 3, v0
	v_lshlrev_b32_e32 v2, 3, v0
	v_cmp_gt_i32_e64 s[44:45], s2, v0
	v_lshl_or_b32 v31, s68, 8, v6
	s_movk_i32 s2, 0x104
	v_lshl_or_b32 v9, v8, 4, v9
	v_add_u32_e32 v30, 0, v10
	v_and_b32_e32 v28, 56, v2
	v_mul_lo_u32 v5, v26, s2
	v_mad_u64_u32 v[32:33], s[2:3], v9, s2, v[30:31]
	v_and_b32_e32 v9, 0x3fffff00, v0
	v_lshlrev_b32_e32 v3, 4, v0
	v_lshl_add_u32 v35, v28, 2, 0
	v_lshl_add_u32 v9, v9, 2, 0
	v_lshlrev_b32_e32 v11, 8, v8
	v_lshlrev_b32_e32 v2, 2, v0
	v_and_b32_e32 v4, 0xf00, v3
	v_add_u32_e32 v29, 0, v3
	v_cmp_lt_u32_e64 s[46:47], 63, v0
	v_mul_lo_u32 v3, v0, -12
	v_add3_u32 v33, v9, v11, v10
	v_add_u32_e32 v37, v35, v5
	v_mul_u32_u24_e32 v5, 0x48, v28
	v_cmp_gt_u32_e32 vcc, 64, v0
	v_bfe_u32 v34, v0, 3, 6
	v_and_b32_e32 v36, 7, v0
	v_ashrrev_i32_e32 v10, 9, v0
	v_add_u32_e32 v0, 0x200, v0
	v_cmp_eq_u32_e64 s[48:49], 0, v8
	v_cmp_ne_u32_e64 s[50:51], 0, v8
	v_cmp_gt_u32_e64 s[52:53], 2, v8
	v_cmp_eq_u32_e64 s[54:55], 3, v8
	v_cmp_ne_u32_e64 s[56:57], 3, v8
	v_cmp_lt_u32_e64 s[58:59], 1, v8
	v_lshlrev_b32_e32 v8, 1, v26
	v_lshlrev_b32_e32 v5, 1, v5
	v_ashrrev_i32_e32 v0, 9, v0
	v_add3_u32 v64, 0, v8, v5
	v_add_u32_e32 v5, 0, v5
	v_lshl_or_b32 v11, v10, 6, v34
	s_movk_i32 s2, 0x90
	v_lshlrev_b32_e32 v38, 8, v10
	v_lshl_or_b32 v10, v0, 6, v34
	v_and_b32_e32 v2, 60, v2
	v_add_u32_e32 v65, v5, v8
	v_mul_i32_i24_e32 v8, 0xffffff74, v28
	v_cndmask_b32_e32 v9, v196, v197, vcc
	v_lshlrev_b32_e32 v74, 5, v7
	v_lshl_add_u32 v7, v36, 4, 0
	v_mul_lo_u32 v11, v11, s2
	v_mul_lo_u32 v10, v10, s2
	v_lshlrev_b32_e32 v40, 8, v0
	s_lshl_b32 s38, s68, 12
	s_mov_b32 s39, s9
	v_ashrrev_i32_e32 v27, 31, v26
	v_add_u32_e32 v66, 0x90, v65
	v_add_u32_e32 v67, 0x120, v65
	v_add_u32_e32 v68, 0x1b0, v65
	v_add_u32_e32 v69, 0x240, v65
	v_add_u32_e32 v70, 0x2d0, v65
	v_add_u32_e32 v71, 0x360, v65
	v_add_u32_e32 v72, 0x3f0, v64
	v_add_u32_e32 v73, 0x3f0, v65
	v_ashrrev_i32_e32 v39, 31, v38
	v_ashrrev_i32_e32 v41, 31, v40
	s_mov_b32 s29, -1
	v_lshlrev_b32_e32 v42, 2, v4
	v_lshlrev_b32_e32 v44, 2, v2
	v_add_u32_e32 v75, v29, v3
	v_add_u32_e32 v76, v5, v8
	v_add_u32_e32 v77, v30, v9
	v_lshlrev_b32_e32 v46, 2, v6
	v_add_u32_e32 v78, v7, v11
	v_add_u32_e32 v79, v7, v10
	v_readlane_b32 s10, v244, 6
	s_mov_b32 s99, 0x7fffffff
	s_branch .LBB0_560

; DI float bflo(unsigned w) { return __uint_as_float(w << 16); }
; DI float bfhi(unsigned w) { return __uint_as_float(w & 0xffff0000u); }
;     DI void operator()(const f32x4 (&acc)[2][2][4][2], const pg8::Unit& u, int wr, int wc, int fr, int fq) const {
;         const int row0 = u.pm * 256 + wr * 64 + fr, col0 = u.pn * 256 + wc * 32 + 8 * fq;
; #pragma unroll
;         for (int ai = 0; ai < 2; ++ai)
; #pragma unroll
;             for (int m = 0; m < 4; ++m) {
;                 const int row = row0 + ai * 128 + m * 16; float ss = 0.f;
; #pragma unroll
;                 for (int bj = 0; bj < 2; ++bj) {
;                     const size_t off = (size_t)row * DM + col0 + bj * 128;
;                     f32x4 b0, b1;
;                     if (base32) { b0 = *(const f32x4*)(base32 + off); b1 = *(const f32x4*)(base32 + off + 4); }
;                     else { const u32x4 bb = *(const u32x4*)(XB + off); b0 = (f32x4){bflo(bb.x), bfhi(bb.x), bflo(bb.y), bfhi(bb.y)}; b1 = (f32x4){bflo(bb.z), bfhi(bb.z), bflo(bb.w), bfhi(bb.w)}; }
.Lkexit_4:
	v_lshl_add_u32 v160, s10, 8, v146
	v_ashrrev_i32_e32 v161, 31, v160
	v_lshl_or_b32 v162, s8, 8, v148
	v_ashrrev_i32_e32 v163, 31, v162
	v_lshlrev_b64 v[160:161], 10, v[160:161]
	v_lshl_add_u64 v[160:161], v[160:161], 0, v[162:163]
	v_lshl_add_u64 v[160:161], v[160:161], 1, s[86:87]
	global_load_dwordx4 v[178:181], v[160:161], off
	global_load_dwordx4 v[182:185], v[160:161], off offset:256
	s_mov_b64 vcc, 0x8000
	v_lshl_add_u64 v[162:163], v[160:161], 0, vcc
	global_load_dwordx4 v[186:189], v[162:163], off
	global_load_dwordx4 v[202:205], v[162:163], off offset:256
	s_mov_b64 vcc, 0x10000
	v_lshl_add_u64 v[162:163], v[160:161], 0, vcc
	global_load_dwordx4 v[206:209], v[162:163], off
	global_load_dwordx4 v[210:213], v[162:163], off offset:256
	s_mov_b64 vcc, 0x18000
	v_lshl_add_u64 v[162:163], v[160:161], 0, vcc
	global_load_dwordx4 v[214:217], v[162:163], off
	global_load_dwordx4 v[218:221], v[162:163], off offset:256
	s_mov_b64 vcc, 0x40000
	v_lshl_add_u64 v[162:163], v[160:161], 0, vcc
	global_load_dwordx4 v[222:225], v[162:163], off
	global_load_dwordx4 v[226:229], v[162:163], off offset:256
	s_mov_b64 vcc, 0x48000
	v_lshl_add_u64 v[162:163], v[160:161], 0, vcc
	global_load_dwordx4 v[230:233], v[162:163], off
	global_load_dwordx4 v[234:237], v[162:163], off offset:256
	s_and_b64 vcc, exec, s[46:47]
	s_cbranch_vccz .LBB0_1019
	s_barrier
	s_setprio 2
